# phase 0 down to exactly 5 static rounds: 512 w_up transposes done one per workgroup at the start of phase 1 (plus v075's moves); prologue waits for the gain-vector LDS-DMA since a row item can now be
# speedup vs baseline: 1.0177x; 1.0039x over previous
.LBB0_33:
	s_or_b64 exec, exec, s[4:5]
	v_writelane_b32 v252, s60, 8
	s_cmpk_gt_i32 s2, 0xe2f
	v_and_b32_e32 v161, 63, v162
	v_writelane_b32 v252, s61, 9
	v_writelane_b32 v252, s62, 10
	v_writelane_b32 v252, s63, 11
	v_writelane_b32 v252, s64, 12
	v_writelane_b32 v252, s65, 13
	v_writelane_b32 v252, s66, 14
	v_writelane_b32 v252, s67, 15
	v_writelane_b32 v252, s68, 16
	v_writelane_b32 v252, s69, 17
	v_writelane_b32 v252, s70, 18
	v_writelane_b32 v252, s71, 19
	v_writelane_b32 v252, s72, 20
	v_writelane_b32 v252, s73, 21
	v_lshrrev_b32_e32 v160, 6, v162
	v_lshrrev_b32_e32 v228, 5, v162
	v_lshlrev_b32_e32 v229, 2, v162
	v_mbcnt_lo_u32_b32 v230, -1, 0
	v_writelane_b32 v252, s74, 22
	v_writelane_b32 v252, s75, 23
	s_cbranch_scc1 .LBB0_59
	s_load_dword s11, s[0:1], 0x1b8
	s_waitcnt lgkmcnt(0)
	s_load_dwordx16 s[12:27], s[0:1], 0xc0
	v_lshlrev_b32_e32 v1, 2, v162
	v_mov_b32_e32 v167, 0
	v_and_b32_e32 v166, 0x7c, v1
	s_movk_i32 s4, 0x84
	s_waitcnt lgkmcnt(0)
	v_lshl_add_u64 v[170:171], s[16:17], 0, v[166:167]
	s_load_dwordx8 s[16:23], s[0:1], 0x180
	v_lshl_add_u64 v[174:175], s[12:13], 0, v[166:167]
	v_lshlrev_b32_e32 v0, 2, v161
	v_lshlrev_b32_e32 v168, 4, v161
	v_mul_u32_u24_e32 v1, 0x74, v161
	s_waitcnt lgkmcnt(0)
	s_mov_b64 s[58:59], s[22:23]
	s_mov_b64 s[56:57], s[20:21]
	s_mov_b64 s[54:55], s[18:19]
	s_mov_b64 s[52:53], s[16:17]
	s_load_dwordx16 s[12:27], s[0:1], 0x80
	v_lshlrev_b32_e32 v2, 2, v160
	v_mad_u32_u24 v231, v228, s4, v166
	s_lshl_b32 s4, s2, 3
	v_mbcnt_hi_u32_b32 v232, -1, v230
	s_waitcnt lgkmcnt(0)
	v_lshl_add_u64 v[178:179], s[24:25], 0, v[166:167]
	v_lshl_add_u64 v[182:183], s[14:15], 0, v[166:167]
	s_load_dwordx16 s[12:27], s[0:1], 0x140
	v_add3_u32 v163, v168, v1, v2
	v_lshlrev_b32_e32 v2, 1, v161
	v_mov_b32_e32 v3, v167
	v_lshl_add_u64 v[186:187], s[36:37], 0, v[166:167]
	v_mov_b32_e32 v169, v167
	v_lshlrev_b32_e32 v166, 3, v161
	s_waitcnt lgkmcnt(0)
	s_add_i32 s12, s4, 0x7ffff000
	s_lshl_b32 s4, s2, 4
	v_lshlrev_b32_e32 v194, 2, v0
	v_and_b32_e32 v0, 64, v232
	v_lshl_add_u64 v[172:173], s[56:57], 0, v[2:3]
	v_lshl_add_u64 v[176:177], s[54:55], 0, v[2:3]
	v_lshl_add_u64 v[180:181], s[52:53], 0, v[2:3]
	v_lshl_add_u64 v[184:185], s[26:27], 0, v[2:3]
	v_lshl_add_u64 v[188:189], s[24:25], 0, v[2:3]
	v_lshl_add_u64 v[190:191], s[74:75], 0, v[168:169]
	v_readfirstlane_b32 s98, v160
	s_nop 3
	s_lshl_b32 s98, s98, 12
	s_add_u32 s98, s98, 0xb000
	s_mov_b32 m0, s98
	v_lshl_add_u32 v250, v161, 4, s98
	global_load_lds_dwordx4 v[190:191], off
	global_load_lds_dwordx4 v[190:191], off offset:1024
	global_load_lds_dwordx4 v[190:191], off offset:2048
	global_load_lds_dwordx4 v[190:191], off offset:3072
	s_waitcnt vmcnt(0)
	v_lshl_add_u64 v[192:193], s[58:59], 0, v[166:167]
	s_add_i32 s13, s4, 0x7fffec00
	v_mov_b32_e32 v169, 0x358637bd
	v_add_u32_e32 v233, 64, v0
	v_xor_b32_e32 v234, 32, v232
	v_xor_b32_e32 v235, 16, v232
	v_xor_b32_e32 v236, 8, v232
	v_xor_b32_e32 v237, 4, v232
	v_xor_b32_e32 v238, 2, v232
	v_xor_b32_e32 v239, 1, v232
	s_lshl_b32 s14, s11, 3
	s_lshl_b32 s15, s11, 8
	s_lshl_b32 s16, s11, 4
	s_movk_i32 s17, 0x4000
	s_mov_b32 s18, 0x800000
	s_mov_b32 s19, 0x10000
	s_mov_b32 s20, 0x28000
	s_mov_b32 s21, 0x50000
	s_mov_b32 s22, 0x58000
	s_mov_b32 s23, 0x78000
	s_mov_b32 s24, 0xa0000
	s_mov_b32 s25, 0xb0000
	s_mov_b32 s26, 0xc8000
	s_mov_b32 s27, 0xf0000
	s_mov_b32 s33, s2
	s_mov_b32 s7, 0
	v_cmp_eq_u32_e64 s[4:5], 0, v161
	s_mov_b32 s32, 0
	s_cmpk_lt_u32 s33, 0x180
	s_cbranch_scc1 .Lp0_a1
	s_addk_i32 s33, 0x2e0
	s_add_i32 s12, s12, 0x1700
	s_add_i32 s10, s10, 0x2e000
	s_add_i32 s13, s13, 0x2e00
	s_mov_b32 s32, 1
.Lp0_a1:
	s_cmp_eq_u32 s32, 1
	s_cbranch_scc0 .Lp0_a2
	s_cmpk_lt_i32 s33, 0x4c0
	s_cbranch_scc1 .Lp0_a2
	s_addk_i32 s33, 0x150
	s_add_i32 s12, s12, 0xa80
	s_add_i32 s10, s10, 0x15000
	s_add_i32 s13, s13, 0x1500
	s_mov_b32 s32, 2
.Lp0_a2:
	s_branch .LBB0_36
.LBB0_35:
	s_add_i32 s33, s33, s11
	s_add_i32 s12, s12, s14
	s_add_i32 s10, s10, s15
	s_add_i32 s13, s13, s16
	s_cmp_eq_u32 s32, 0
	s_cbranch_scc0 .Lp0_b1
	s_addk_i32 s33, 0x2e0
	s_add_i32 s12, s12, 0x1700
	s_add_i32 s10, s10, 0x2e000
	s_add_i32 s13, s13, 0x2e00
	s_mov_b32 s32, 1

.Lp1_task_done:
	s_add_u32 s12, s63, 0x60
	s_lshr_b32 s13, s12, 2
	s_lshl_b32 s13, s13, 5
	s_and_b32 s14, s12, 3
	s_lshl_b32 s14, s14, 8
	s_lshr_b32 s15, s13, 7
	s_lshl_b32 s15, s15, 6
	s_bfe_u32 s18, s13, 0x10006
	s_lshl_b32 s18, s18, 5
	s_add_u32 s15, s15, s18
	s_bfe_u32 s18, s13, 0x10005
	s_mul_i32 s18, s18, 0xb00
	s_add_u32 s15, s15, s18
	s_mov_b32 s16, 0x5800
	s_mov_b32 s17, 0x800
	v_readlane_b32 s20, v251, 40
	v_readlane_b32 s21, v251, 41
	v_readlane_b32 s22, v251, 2
	v_readlane_b32 s23, v251, 3
	s_mul_i32 s18, s14, s16
	s_lshl_b32 s19, s15, 2
	s_add_u32 s18, s18, s19
	s_add_u32 s20, s20, s18
	s_addc_u32 s21, s21, 0
	s_mul_i32 s18, s13, s17
	s_lshl_b32 s19, s14, 1
	s_add_u32 s18, s18, s19
	s_add_u32 s22, s22, s18
	s_addc_u32 s23, s23, 0
	s_lshl_b32 s24, s16, 3
	s_lshl_b32 s25, s17, 2
	v_and_b32_e32 v85, 31, v162
	v_lshrrev_b32_e32 v86, 5, v162
	v_lshlrev_b32_e32 v87, 2, v85
	v_mad_u32_u24 v87, v86, s16, v87
	v_mul_u32_u24_e32 v88, 33, v86
	v_add_lshl_u32 v88, v88, v85, 2
	v_and_b32_e32 v89, 63, v162
	v_lshrrev_b32_e32 v90, 6, v162
	v_mul_u32_u24_e32 v91, 33, v89
	v_add_lshl_u32 v91, v91, v90, 2
	v_lshlrev_b32_e32 v92, 1, v89
	v_mad_u32_u24 v92, v90, s17, v92
	s_waitcnt lgkmcnt(0)
	s_barrier
	s_mov_b64 s[26:27], s[20:21]
	global_load_dword v40, v87, s[26:27]
	s_add_u32 s26, s26, s24
	s_addc_u32 s27, s27, 0
	global_load_dword v41, v87, s[26:27]
	s_add_u32 s26, s26, s24
	s_addc_u32 s27, s27, 0
	global_load_dword v42, v87, s[26:27]
	s_add_u32 s26, s26, s24
	s_addc_u32 s27, s27, 0
	global_load_dword v43, v87, s[26:27]
	s_add_u32 s26, s26, s24
	s_addc_u32 s27, s27, 0
	global_load_dword v44, v87, s[26:27]
	s_add_u32 s26, s26, s24
	s_addc_u32 s27, s27, 0
	global_load_dword v45, v87, s[26:27]
	s_add_u32 s26, s26, s24
	s_addc_u32 s27, s27, 0
	global_load_dword v46, v87, s[26:27]
	s_add_u32 s26, s26, s24
	s_addc_u32 s27, s27, 0
	global_load_dword v47, v87, s[26:27]
	s_add_u32 s26, s26, s24
	s_addc_u32 s27, s27, 0
	global_load_dword v48, v87, s[26:27]
	s_add_u32 s26, s26, s24
	s_addc_u32 s27, s27, 0
	global_load_dword v49, v87, s[26:27]
	s_add_u32 s26, s26, s24
	s_addc_u32 s27, s27, 0
	global_load_dword v50, v87, s[26:27]
	s_add_u32 s26, s26, s24
	s_addc_u32 s27, s27, 0
	global_load_dword v51, v87, s[26:27]
	s_add_u32 s26, s26, s24
	s_addc_u32 s27, s27, 0
	global_load_dword v52, v87, s[26:27]
	s_add_u32 s26, s26, s24
	s_addc_u32 s27, s27, 0
	global_load_dword v53, v87, s[26:27]
	s_add_u32 s26, s26, s24
	s_addc_u32 s27, s27, 0
	global_load_dword v54, v87, s[26:27]
	s_add_u32 s26, s26, s24
	s_addc_u32 s27, s27, 0
	global_load_dword v55, v87, s[26:27]
	s_add_u32 s26, s26, s24
	s_addc_u32 s27, s27, 0
	global_load_dword v56, v87, s[26:27]
	s_add_u32 s26, s26, s24
	s_addc_u32 s27, s27, 0
	global_load_dword v57, v87, s[26:27]
	s_add_u32 s26, s26, s24
	s_addc_u32 s27, s27, 0
	global_load_dword v58, v87, s[26:27]
	s_add_u32 s26, s26, s24
	s_addc_u32 s27, s27, 0
	global_load_dword v59, v87, s[26:27]
	s_add_u32 s26, s26, s24
	s_addc_u32 s27, s27, 0
	global_load_dword v60, v87, s[26:27]
	s_add_u32 s26, s26, s24
	s_addc_u32 s27, s27, 0
	global_load_dword v61, v87, s[26:27]
	s_add_u32 s26, s26, s24
	s_addc_u32 s27, s27, 0
	global_load_dword v62, v87, s[26:27]
	s_add_u32 s26, s26, s24
	s_addc_u32 s27, s27, 0
	global_load_dword v63, v87, s[26:27]
	s_add_u32 s26, s26, s24
	s_addc_u32 s27, s27, 0
	global_load_dword v64, v87, s[26:27]
	s_add_u32 s26, s26, s24
	s_addc_u32 s27, s27, 0
	global_load_dword v65, v87, s[26:27]
	s_add_u32 s26, s26, s24
	s_addc_u32 s27, s27, 0
	global_load_dword v66, v87, s[26:27]
	s_add_u32 s26, s26, s24
	s_addc_u32 s27, s27, 0
	global_load_dword v72, v87, s[26:27]
	s_add_u32 s26, s26, s24
	s_addc_u32 s27, s27, 0
	global_load_dword v73, v87, s[26:27]
	s_add_u32 s26, s26, s24
	s_addc_u32 s27, s27, 0
	global_load_dword v74, v87, s[26:27]
	s_add_u32 s26, s26, s24
	s_addc_u32 s27, s27, 0
	global_load_dword v75, v87, s[26:27]
	s_add_u32 s26, s26, s24
	s_addc_u32 s27, s27, 0
	global_load_dword v76, v87, s[26:27]
	s_waitcnt vmcnt(31)
	ds_write_b32 v88, v40 offset:0
	s_waitcnt vmcnt(30)
	ds_write_b32 v88, v41 offset:1056
	s_waitcnt vmcnt(29)
	ds_write_b32 v88, v42 offset:2112
	s_waitcnt vmcnt(28)
	ds_write_b32 v88, v43 offset:3168
	s_waitcnt vmcnt(27)
	ds_write_b32 v88, v44 offset:4224
	s_waitcnt vmcnt(26)
	ds_write_b32 v88, v45 offset:5280
	s_waitcnt vmcnt(25)
	ds_write_b32 v88, v46 offset:6336
	s_waitcnt vmcnt(24)
	ds_write_b32 v88, v47 offset:7392
	s_waitcnt lgkmcnt(0)
	s_barrier
	ds_read_b32 v77, v91 offset:0
	ds_read_b32 v78, v91 offset:16
	ds_read_b32 v79, v91 offset:32
	ds_read_b32 v80, v91 offset:48
	ds_read_b32 v81, v91 offset:64
	ds_read_b32 v82, v91 offset:80
	ds_read_b32 v83, v91 offset:96
	ds_read_b32 v84, v91 offset:112
	s_mov_b64 s[64:65], s[22:23]
	s_waitcnt lgkmcnt(7)
	v_cvt_pk_bf16_f32 v77, v77, v77
	global_store_short v92, v77, s[64:65] offset:0
	s_add_u32 s64, s64, s25
	s_addc_u32 s65, s65, 0
	s_waitcnt lgkmcnt(6)
	v_cvt_pk_bf16_f32 v78, v78, v78
	global_store_short v92, v78, s[64:65] offset:0
	s_add_u32 s64, s64, s25
	s_addc_u32 s65, s65, 0
	s_waitcnt lgkmcnt(5)
	v_cvt_pk_bf16_f32 v79, v79, v79
	global_store_short v92, v79, s[64:65] offset:0
	s_add_u32 s64, s64, s25
	s_addc_u32 s65, s65, 0
	s_waitcnt lgkmcnt(4)
	v_cvt_pk_bf16_f32 v80, v80, v80
	global_store_short v92, v80, s[64:65] offset:0
	s_add_u32 s64, s64, s25
	s_addc_u32 s65, s65, 0
	s_waitcnt lgkmcnt(3)
	v_cvt_pk_bf16_f32 v81, v81, v81
	global_store_short v92, v81, s[64:65] offset:0
	s_add_u32 s64, s64, s25
	s_addc_u32 s65, s65, 0
	s_waitcnt lgkmcnt(2)
	v_cvt_pk_bf16_f32 v82, v82, v82
	global_store_short v92, v82, s[64:65] offset:0
	s_add_u32 s64, s64, s25
	s_addc_u32 s65, s65, 0
	s_waitcnt lgkmcnt(1)
	v_cvt_pk_bf16_f32 v83, v83, v83
	global_store_short v92, v83, s[64:65] offset:0
	s_add_u32 s64, s64, s25
	s_addc_u32 s65, s65, 0
	s_waitcnt lgkmcnt(0)
	v_cvt_pk_bf16_f32 v84, v84, v84
	global_store_short v92, v84, s[64:65] offset:0
	s_barrier
	s_waitcnt vmcnt(31)
	ds_write_b32 v88, v48 offset:0
	s_waitcnt vmcnt(30)
	ds_write_b32 v88, v49 offset:1056
	s_waitcnt vmcnt(29)
	ds_write_b32 v88, v50 offset:2112
	s_waitcnt vmcnt(28)
	ds_write_b32 v88, v51 offset:3168
	s_waitcnt vmcnt(27)
	ds_write_b32 v88, v52 offset:4224
	s_waitcnt vmcnt(26)
	ds_write_b32 v88, v53 offset:5280
	s_waitcnt vmcnt(25)
	ds_write_b32 v88, v54 offset:6336
	s_waitcnt vmcnt(24)
	ds_write_b32 v88, v55 offset:7392
	s_waitcnt lgkmcnt(0)
	s_barrier
	ds_read_b32 v77, v91 offset:0
	ds_read_b32 v78, v91 offset:16
	ds_read_b32 v79, v91 offset:32
	ds_read_b32 v80, v91 offset:48
	ds_read_b32 v81, v91 offset:64
	ds_read_b32 v82, v91 offset:80
	ds_read_b32 v83, v91 offset:96
	ds_read_b32 v84, v91 offset:112
	s_mov_b64 s[64:65], s[22:23]
	s_waitcnt lgkmcnt(7)
	v_cvt_pk_bf16_f32 v77, v77, v77
	global_store_short v92, v77, s[64:65] offset:128
	s_add_u32 s64, s64, s25
	s_addc_u32 s65, s65, 0
	s_waitcnt lgkmcnt(6)
	v_cvt_pk_bf16_f32 v78, v78, v78
	global_store_short v92, v78, s[64:65] offset:128
	s_add_u32 s64, s64, s25
	s_addc_u32 s65, s65, 0
	s_waitcnt lgkmcnt(5)
	v_cvt_pk_bf16_f32 v79, v79, v79
	global_store_short v92, v79, s[64:65] offset:128
	s_add_u32 s64, s64, s25
	s_addc_u32 s65, s65, 0
	s_waitcnt lgkmcnt(4)
	v_cvt_pk_bf16_f32 v80, v80, v80
	global_store_short v92, v80, s[64:65] offset:128
	s_add_u32 s64, s64, s25
	s_addc_u32 s65, s65, 0
	s_waitcnt lgkmcnt(3)
	v_cvt_pk_bf16_f32 v81, v81, v81
	global_store_short v92, v81, s[64:65] offset:128
	s_add_u32 s64, s64, s25
	s_addc_u32 s65, s65, 0
	s_waitcnt lgkmcnt(2)
	v_cvt_pk_bf16_f32 v82, v82, v82
	global_store_short v92, v82, s[64:65] offset:128
	s_add_u32 s64, s64, s25
	s_addc_u32 s65, s65, 0
	s_waitcnt lgkmcnt(1)
	v_cvt_pk_bf16_f32 v83, v83, v83
	global_store_short v92, v83, s[64:65] offset:128
	s_add_u32 s64, s64, s25
	s_addc_u32 s65, s65, 0
	s_waitcnt lgkmcnt(0)
	v_cvt_pk_bf16_f32 v84, v84, v84
	global_store_short v92, v84, s[64:65] offset:128
	s_barrier
	s_waitcnt vmcnt(31)
	ds_write_b32 v88, v56 offset:0
	s_waitcnt vmcnt(30)
	ds_write_b32 v88, v57 offset:1056
	s_waitcnt vmcnt(29)
	ds_write_b32 v88, v58 offset:2112
	s_waitcnt vmcnt(28)
	ds_write_b32 v88, v59 offset:3168
	s_waitcnt vmcnt(27)
	ds_write_b32 v88, v60 offset:4224
	s_waitcnt vmcnt(26)
	ds_write_b32 v88, v61 offset:5280
	s_waitcnt vmcnt(25)
	ds_write_b32 v88, v62 offset:6336
	s_waitcnt vmcnt(24)
	ds_write_b32 v88, v63 offset:7392
	s_waitcnt lgkmcnt(0)
	s_barrier
	ds_read_b32 v77, v91 offset:0
	ds_read_b32 v78, v91 offset:16
	ds_read_b32 v79, v91 offset:32
	ds_read_b32 v80, v91 offset:48
	ds_read_b32 v81, v91 offset:64
	ds_read_b32 v82, v91 offset:80
	ds_read_b32 v83, v91 offset:96
	ds_read_b32 v84, v91 offset:112
	s_mov_b64 s[64:65], s[22:23]
	s_waitcnt lgkmcnt(7)
	v_cvt_pk_bf16_f32 v77, v77, v77
	global_store_short v92, v77, s[64:65] offset:256
	s_add_u32 s64, s64, s25
	s_addc_u32 s65, s65, 0
	s_waitcnt lgkmcnt(6)
	v_cvt_pk_bf16_f32 v78, v78, v78
	global_store_short v92, v78, s[64:65] offset:256
	s_add_u32 s64, s64, s25
	s_addc_u32 s65, s65, 0
	s_waitcnt lgkmcnt(5)
	v_cvt_pk_bf16_f32 v79, v79, v79
	global_store_short v92, v79, s[64:65] offset:256
	s_add_u32 s64, s64, s25
	s_addc_u32 s65, s65, 0
	s_waitcnt lgkmcnt(4)
	v_cvt_pk_bf16_f32 v80, v80, v80
	global_store_short v92, v80, s[64:65] offset:256
	s_add_u32 s64, s64, s25
	s_addc_u32 s65, s65, 0
	s_waitcnt lgkmcnt(3)
	v_cvt_pk_bf16_f32 v81, v81, v81
	global_store_short v92, v81, s[64:65] offset:256
	s_add_u32 s64, s64, s25
	s_addc_u32 s65, s65, 0
	s_waitcnt lgkmcnt(2)
	v_cvt_pk_bf16_f32 v82, v82, v82
	global_store_short v92, v82, s[64:65] offset:256
	s_add_u32 s64, s64, s25
	s_addc_u32 s65, s65, 0
	s_waitcnt lgkmcnt(1)
	v_cvt_pk_bf16_f32 v83, v83, v83
	global_store_short v92, v83, s[64:65] offset:256
	s_add_u32 s64, s64, s25
	s_addc_u32 s65, s65, 0
	s_waitcnt lgkmcnt(0)
	v_cvt_pk_bf16_f32 v84, v84, v84
	global_store_short v92, v84, s[64:65] offset:256
	s_barrier
	s_waitcnt vmcnt(31)
	ds_write_b32 v88, v64 offset:0
	s_waitcnt vmcnt(30)
	ds_write_b32 v88, v65 offset:1056
	s_waitcnt vmcnt(29)
	ds_write_b32 v88, v66 offset:2112
	s_waitcnt vmcnt(28)
	ds_write_b32 v88, v72 offset:3168
	s_waitcnt vmcnt(27)
	ds_write_b32 v88, v73 offset:4224
	s_waitcnt vmcnt(26)
	ds_write_b32 v88, v74 offset:5280
	s_waitcnt vmcnt(25)
	ds_write_b32 v88, v75 offset:6336
	s_waitcnt vmcnt(24)
	ds_write_b32 v88, v76 offset:7392
	s_waitcnt lgkmcnt(0)
	s_barrier
	ds_read_b32 v77, v91 offset:0
	ds_read_b32 v78, v91 offset:16
	ds_read_b32 v79, v91 offset:32
	ds_read_b32 v80, v91 offset:48
	ds_read_b32 v81, v91 offset:64
	ds_read_b32 v82, v91 offset:80
	ds_read_b32 v83, v91 offset:96
	ds_read_b32 v84, v91 offset:112
	s_mov_b64 s[64:65], s[22:23]
	s_waitcnt lgkmcnt(7)
	v_cvt_pk_bf16_f32 v77, v77, v77
	global_store_short v92, v77, s[64:65] offset:384
	s_add_u32 s64, s64, s25
	s_addc_u32 s65, s65, 0
	s_waitcnt lgkmcnt(6)
	v_cvt_pk_bf16_f32 v78, v78, v78
	global_store_short v92, v78, s[64:65] offset:384
	s_add_u32 s64, s64, s25
	s_addc_u32 s65, s65, 0
	s_waitcnt lgkmcnt(5)
	v_cvt_pk_bf16_f32 v79, v79, v79
	global_store_short v92, v79, s[64:65] offset:384
	s_add_u32 s64, s64, s25
	s_addc_u32 s65, s65, 0
	s_waitcnt lgkmcnt(4)
	v_cvt_pk_bf16_f32 v80, v80, v80
	global_store_short v92, v80, s[64:65] offset:384
	s_add_u32 s64, s64, s25
	s_addc_u32 s65, s65, 0
	s_waitcnt lgkmcnt(3)
	v_cvt_pk_bf16_f32 v81, v81, v81
	global_store_short v92, v81, s[64:65] offset:384
	s_add_u32 s64, s64, s25
	s_addc_u32 s65, s65, 0
	s_waitcnt lgkmcnt(2)
	v_cvt_pk_bf16_f32 v82, v82, v82
	global_store_short v92, v82, s[64:65] offset:384
	s_add_u32 s64, s64, s25
	s_addc_u32 s65, s65, 0
	s_waitcnt lgkmcnt(1)
	v_cvt_pk_bf16_f32 v83, v83, v83
	global_store_short v92, v83, s[64:65] offset:384
	s_add_u32 s64, s64, s25
	s_addc_u32 s65, s65, 0
	s_waitcnt lgkmcnt(0)
	v_cvt_pk_bf16_f32 v84, v84, v84
	global_store_short v92, v84, s[64:65] offset:384
	s_barrier
	v_lshrrev_b32_e32 v112, 3, v162
	v_xor_b32_e32 v2, v112, v162
	s_movk_i32 s3, 0x1c0
	v_lshlrev_b32_e32 v2, 4, v2
	v_and_or_b32 v99, v100, s3, v98
	v_bitop3_b32 v3, v101, v219, 3 bitop3:0x6c
	v_lshlrev_b32_e32 v4, 7, v112
	s_movk_i32 s3, 0x70
	v_and_b32_e32 v0, 56, v97
	v_mov_b32_e32 v1, 0
	v_lshlrev_b32_e32 v6, 7, v99
	v_lshlrev_b32_e32 v7, 4, v3
	v_and_or_b32 v103, v2, s3, v4
	v_and_b32_e32 v8, 0x2780, v137
	v_lshlrev_b32_e32 v9, 4, v138
	v_and_b32_e32 v3, 64, v162
	v_and_b32_e32 v2, 12, v139
	s_cbranch_execz .LBB0_125
	s_branch .LBB0_126
